# attention sample items moved to the 16 workgroups whose prompt items are short (n=0,1 chunks)
# speedup vs baseline: 1.0126x; 1.0126x over previous
.LBB0_91:
	s_cmp_lg_u32 s25, 0x100
	s_cbranch_scc1 .Lat_orig
	s_and_b64 vcc, exec, s[82:83]
	s_cbranch_vccz .Lat_orig
	s_and_b32 s101, s80, 0x7f
	s_cmp_lt_u32 s101, 0x78
	s_cbranch_scc1 .LBB0_106
	s_lshr_b32 s100, s80, 7
	s_lshl_b32 s100, s100, 2
	s_cmp_lt_u32 s101, 0x7c
	s_cbranch_scc1 .Lat_n1
	s_sub_i32 s101, s101, 0x7c
	s_add_i32 s101, s101, s100
	s_mul_i32 s37, s101, 6
	s_add_i32 s100, s37, 6
	s_mov_b32 s101, 1
	s_branch .Lat_go
.Lat_n1:
	s_sub_i32 s101, s101, 0x78
	s_add_i32 s101, s101, s100
	s_lshl_b32 s37, s101, 1
	s_add_i32 s37, s37, 48
	s_add_i32 s100, s37, 2
	s_mov_b32 s101, 1
	s_branch .Lat_go
.Lat_orig:
	s_cmp_gt_i32 s80, 63
	s_cbranch_scc1 .LBB0_106
	s_mov_b32 s37, s80
	s_mov_b32 s100, 64
	s_mov_b32 s101, s25
.Lat_go:
	v_readlane_b32 s6, v252, 30
	v_readlane_b32 s7, v252, 31
	s_lshl_b64 s[6:7], s[6:7], 21
	s_add_u32 s8, s22, s6
	s_addc_u32 s9, s23, s7
	s_add_u32 s2, s2, s6
	v_or_b32_e32 v1, 0x80, v189
	s_addc_u32 s3, s3, s7
	v_sub_u32_e32 v1, v1, v98
	s_movk_i32 s6, 0x500
	s_cmp_eq_u32 s30, 0
	v_lshl_add_u32 v0, v190, 4, 0
	s_waitcnt vmcnt(9)
	v_cvt_f32_ubyte0_e32 v116, v1
	v_add3_u32 v1, 0, v191, v192
	v_mul_u32_u24_e32 v2, 0xc0, v193
	v_and_b32_e32 v117, 56, v188
	v_or_b32_e32 v93, 0x10000, v189
	v_cmp_gt_i32_e64 s[6:7], s6, v181
	s_cselect_b64 s[22:23], -1, 0
	v_lshl_add_u32 v92, v117, 1, 0
	v_lshlrev_b32_e32 v96, 1, v180
	v_lshlrev_b32_e32 v94, 1, v98
	v_add_u32_e32 v118, v0, v99
	v_add_u32_e32 v119, v1, v2
	s_nop 0
	s_branch .LBB0_94
.LBB0_93:
	s_add_i32 s37, s37, s101
	s_cmp_lt_i32 s37, s100
	s_cbranch_scc0 .LBB0_106

	.amdhsa_kernel _Z6mk_fwd4Args
		.amdhsa_group_segment_fixed_size 0
		.amdhsa_private_segment_fixed_size 0
		.amdhsa_kernarg_size 424
		.amdhsa_user_sgpr_count 2
		.amdhsa_user_sgpr_dispatch_ptr 0
		.amdhsa_user_sgpr_queue_ptr 0
		.amdhsa_user_sgpr_kernarg_segment_ptr 1
		.amdhsa_user_sgpr_dispatch_id 0
		.amdhsa_user_sgpr_kernarg_preload_length 0
		.amdhsa_user_sgpr_kernarg_preload_offset 0
		.amdhsa_user_sgpr_private_segment_size 0
		.amdhsa_uses_dynamic_stack 0
		.amdhsa_enable_private_segment 0
		.amdhsa_system_sgpr_workgroup_id_x 1
		.amdhsa_system_sgpr_workgroup_id_y 0
		.amdhsa_system_sgpr_workgroup_id_z 0
		.amdhsa_system_sgpr_workgroup_info 0
		.amdhsa_system_vgpr_workitem_id 2
		.amdhsa_next_free_vgpr 253
		.amdhsa_next_free_sgpr 102
		.amdhsa_accum_offset 256
		.amdhsa_reserve_vcc 1
		.amdhsa_float_round_mode_32 0
		.amdhsa_float_round_mode_16_64 0
		.amdhsa_float_denorm_mode_32 3
		.amdhsa_float_denorm_mode_16_64 3
		.amdhsa_dx10_clamp 1
		.amdhsa_ieee_mode 1
		.amdhsa_fp16_overflow 0
		.amdhsa_tg_split 0
		.amdhsa_exception_fp_ieee_invalid_op 0
		.amdhsa_exception_fp_denorm_src 0
		.amdhsa_exception_fp_ieee_div_zero 0
		.amdhsa_exception_fp_ieee_overflow 0
		.amdhsa_exception_fp_ieee_underflow 0
		.amdhsa_exception_fp_ieee_inexact 0
		.amdhsa_exception_int_div_zero 0
	.end_amdhsa_kernel

amdhsa.kernels:
  - .agpr_count:     0
    .args:
      - .offset:         0
        .size:           168
        .value_kind:     by_value
      - .offset:         168
        .size:           4
        .value_kind:     hidden_block_count_x
      - .offset:         172
        .size:           4
        .value_kind:     hidden_block_count_y
      - .offset:         176
        .size:           4
        .value_kind:     hidden_block_count_z
      - .offset:         180
        .size:           2
        .value_kind:     hidden_group_size_x
      - .offset:         182
        .size:           2
        .value_kind:     hidden_group_size_y
      - .offset:         184
        .size:           2
        .value_kind:     hidden_group_size_z
      - .offset:         186
        .size:           2
        .value_kind:     hidden_remainder_x
      - .offset:         188
        .size:           2
        .value_kind:     hidden_remainder_y
      - .offset:         190
        .size:           2
        .value_kind:     hidden_remainder_z
      - .offset:         208
        .size:           8
        .value_kind:     hidden_global_offset_x
      - .offset:         216
        .size:           8
        .value_kind:     hidden_global_offset_y
      - .offset:         224
        .size:           8
        .value_kind:     hidden_global_offset_z
      - .offset:         232
        .size:           2
        .value_kind:     hidden_grid_dims
      - .offset:         256
        .size:           8
        .value_kind:     hidden_multigrid_sync_arg
      - .offset:         288
        .size:           4
        .value_kind:     hidden_dynamic_lds_size
    .group_segment_fixed_size: 0
    .kernarg_segment_align: 8
    .kernarg_segment_size: 424
    .language:       OpenCL C
    .language_version:
      - 2
      - 0
    .max_flat_workgroup_size: 512
    .name:           _Z6mk_fwd4Args
    .private_segment_fixed_size: 0
    .sgpr_count:     108
    .sgpr_spill_count: 57
    .symbol:         _Z6mk_fwd4Args.kd
    .uniform_work_group_size: 1
    .uses_dynamic_stack: false
    .vgpr_count:     253
    .vgpr_spill_count: 0
    .wavefront_size: 64
